# combo20 with the static K-loop priority on the younger wave half (waves 4-7) instead of the older half
# baseline (speedup 1.0000x reference)
; template <class Epi>
; __device__ __forceinline__ void gemm_phase(LAS unsigned char* lds, const Gemm g, const StaticOrder& S, const Epi& E, const int tid) {
;     ...
;         const bool has_next = S.next(ui + 1, nxt);
;         const char* nA = has_next ? PG8_APTR(nxt) : cA; const char* nB = has_next ? PG8_BPTR(nxt) : cB;
;         for (int t = 0; t < nt; t += 2) {
;             const bool last = (t == nt - 2);
;             const char* a1 = cA + (size_t)(t + 1) * kstep;
;             const char* a2 = last ? nA : cA + (size_t)(t + 2) * kstep; const char* b2 = last ? nB : cB + (size_t)(t + 2) * kstep;
.LBB0_160:
	s_ashr_i32 s15, s14, 31
	s_lshl_b64 s[16:17], s[14:15], 20
	s_add_u32 s16, s58, s16
	s_addc_u32 s17, s59, s17
	s_and_b64 s[18:19], s[36:37], exec
	s_cselect_b32 s15, s17, s35
	s_cselect_b32 s53, s16, s34
	s_ashr_i32 s13, s12, 31
	s_lshl_b64 s[18:19], s[12:13], 20
	s_add_u32 s18, s40, s18
	s_addc_u32 s19, s41, s19
	s_and_b64 s[38:39], s[36:37], exec
	s_cselect_b32 s13, s19, s1
	s_cselect_b32 s56, s18, s0
	s_add_u32 s34, s34, 0x80080
	s_addc_u32 s35, s35, 0
	s_add_u32 s57, s0, 0x100
	s_addc_u32 s58, s1, 0
	s_mov_b32 s59, -2
	s_cmp_lg_u64 s[10:11], 0
	s_cbranch_scc1 .Lgprio_a
	s_setprio 1

; template <class Epi>
; __device__ __forceinline__ void gemm_phase(LAS unsigned char* lds, const Gemm g, const StaticOrder& S, const Epi& E, const int tid) {
;     ...
;         const bool has_next = S.next(ui + 1, nxt);
;         const char* nA = has_next ? PG8_APTR(nxt) : cA; const char* nB = has_next ? PG8_BPTR(nxt) : cB;
;         for (int t = 0; t < nt; t += 2) {
.LBB0_232:
	s_add_u32 s42, s0, 0x100
	s_addc_u32 s43, s1, 0
	s_mov_b32 s69, -2
	s_cmp_lg_u64 s[10:11], 0
	s_cbranch_scc1 .Lgprio_b
	s_setprio 1

; template <class Epi>
; __device__ __forceinline__ void gemm_phase(LAS unsigned char* lds, const Gemm g, const StaticOrder& S, const Epi& E, const int tid) {
;     ...
;         const bool has_next = S.next(ui + 1, nxt);
;         const char* nA = has_next ? PG8_APTR(nxt) : cA; const char* nB = has_next ? PG8_BPTR(nxt) : cB;
;         for (int t = 0; t < nt; t += 2) {
.LBB0_353:
	s_ashr_i32 s49, s48, 31
	s_lshl_b64 s[10:11], s[48:49], 20
	s_add_u32 s52, s38, s10
	s_addc_u32 s53, s39, s11
	s_and_b64 s[10:11], s[40:41], exec
	s_cselect_b32 s10, s53, s1
	s_cselect_b32 s11, s52, s0
	s_ashr_i32 s47, s46, 31
	s_lshl_b64 s[12:13], s[46:47], 20
	v_readlane_b32 s16, v255, 32
	s_add_u32 s12, s16, s12
	v_readlane_b32 s16, v255, 33
	s_addc_u32 s13, s16, s13
	s_and_b64 s[36:37], s[40:41], exec
	s_cselect_b32 s47, s13, s43
	s_cselect_b32 s49, s12, s42
	s_add_u32 s36, s0, 0x80080
	s_addc_u32 s37, s1, 0
	s_add_u32 s69, s42, 0x100
	s_addc_u32 vcc_lo, s43, 0
	s_mov_b32 vcc_hi, -2
	s_cmp_lg_u64 s[34:35], 0
	s_cbranch_scc1 .Lgprio_c
	s_setprio 1

; template <class Epi>
; __device__ __forceinline__ void gemm_phase(LAS unsigned char* lds, const Gemm g, const StaticOrder& S, const Epi& E, const int tid) {
;     ...
;         const bool has_next = S.next(ui + 1, nxt);
;         const char* nA = has_next ? PG8_APTR(nxt) : cA; const char* nB = has_next ? PG8_BPTR(nxt) : cB;
;         for (int t = 0; t < nt; t += 2) {
.LBB0_1003:
	s_ashr_i32 s13, s12, 31
	s_lshl_b64 s[14:15], s[12:13], 20
	s_add_u32 s14, s58, s14
	s_addc_u32 s15, s59, s15
	s_and_b64 s[16:17], s[38:39], exec
	s_cselect_b32 s13, s15, s19
	s_cselect_b32 s49, s14, s18
	s_ashr_i32 s11, s10, 31
	s_lshl_b64 s[16:17], s[10:11], 20
	s_add_u32 s16, s36, s16
	s_addc_u32 s17, s37, s17
	s_and_b64 s[24:25], s[38:39], exec
	s_cselect_b32 s11, s17, s1
	s_cselect_b32 s52, s16, s0
	s_add_u32 s18, s18, 0x80080
	s_addc_u32 s19, s19, 0
	s_add_u32 s53, s0, 0x100
	s_addc_u32 s56, s1, 0
	s_mov_b32 s57, -2
	s_cmp_lg_u64 s[8:9], 0
	s_cbranch_scc1 .Lgprio_f
	s_setprio 1

; template <class Epi>
; __device__ __forceinline__ void gemm_phase(LAS unsigned char* lds, const Gemm g, const StaticOrder& S, const Epi& E, const int tid) {
;     ...
;         const bool has_next = S.next(ui + 1, nxt);
;         const char* nA = has_next ? PG8_APTR(nxt) : cA; const char* nB = has_next ? PG8_BPTR(nxt) : cB;
;         for (int t = 0; t < nt; t += 2) {
.LBB0_1075:
	s_add_u32 s38, s0, 0x100
	s_addc_u32 s39, s1, 0
	s_mov_b32 s53, -2
	s_cmp_lg_u64 s[6:7], 0
	s_cbranch_scc1 .Lgprio_g
	s_setprio 1
